# conversion work-list rebalancing: layer-0 O-proj weight conversion (2048 items) leaves the HBM-bound prologue and joins the layer-0 QKV phase's idle tail; on attention zero-hoist stack
# speedup vs baseline: 1.0023x; 1.0023x over previous
.LBB0_16:
	s_mov_b64 s[10:11], s[42:43]
	s_mov_b32 s5, s63
	s_mov_b32 s4, s2
	s_mov_b64 s[6:7], s[40:41]
	s_mov_b32 s8, s52
	v_mbcnt_lo_u32_b32 v2, -1, 0
	v_mbcnt_hi_u32_b32 v2, -1, v2
	s_lshl_b32 s7, s8, 3
	v_lshl_add_u32 v1, s4, 6, v2
	s_nop 0
	v_readfirstlane_b32 s4, v1
	s_ashr_i32 s6, s4, 6
	s_add_i32 s20, s6, s7
	s_cmpk_gt_i32 s20, 0x11ff
	s_cbranch_scc1 .LBB0_56
	s_lshl_b32 s21, s5, 3
	s_lshl_b32 s5, s6, 14
	s_add_i32 s22, s5, 0
	s_add_u32 s23, s10, 0x100000
	v_and_b32_e32 v3, 63, v2
	v_bfe_u32 v1, v2, 3, 3
	v_and_b32_e32 v5, 7, v2
	s_addc_u32 s24, s11, 0
	s_bfe_u32 s25, s4, 0x30006
	v_lshlrev_b32_e32 v14, 2, v3
	v_lshl_add_u32 v7, v5, 4, s22
	v_mul_u32_u24_e32 v8, 0x84, v1
	v_lshlrev_b32_e32 v2, 3, v5
	v_mul_u32_u24_e32 v5, 0x420, v5
	v_lshlrev_b32_e32 v6, 2, v1
	s_lshl_b32 s26, s25, 8
	v_and_b32_e32 v4, 28, v14
	v_and_b32_e32 v26, 16, v6
	v_add3_u32 v27, s22, v5, v6
	v_add_u32_e32 v28, s22, v14
	v_or_b32_e32 v31, 12, v6
	v_or_b32_e32 v6, s26, v3
	v_mov_b32_e32 v5, 0x800
	v_add_u32_e32 v35, v7, v8
	s_mov_b32 s13, 0
	v_mov_b32_e32 v17, 0
	v_or_b32_e32 v15, 8, v1
	v_or_b32_e32 v24, 16, v1
	v_or_b32_e32 v25, 24, v1
	v_or_b32_e32 v29, 4, v26
	v_or_b32_e32 v30, 8, v26
	s_or_b32 s27, s26, 0xfffff800
	v_or_b32_e32 v32, 0xc0, v3
	v_add_u32_e32 v33, 0x400, v28
	v_lshl_or_b32 v34, v3, 3, v5
	v_lshlrev_b32_e32 v18, 2, v4
	v_add_u32_e32 v36, 0x420, v35
	v_add_u32_e32 v37, 0x428, v35
	v_add_u32_e32 v38, 0x840, v35
	v_add_u32_e32 v39, 0x848, v35
	v_add_u32_e32 v40, 0xc60, v35
	v_add_u32_e32 v41, 0xc68, v35
	v_add_u32_e32 v42, 0x1080, v35
	v_add_u32_e32 v43, 0x1088, v35
	v_add_u32_e32 v44, 0x14a0, v35
	v_add_u32_e32 v45, 0x14a8, v35
	v_add_u32_e32 v46, 0x18c0, v35
	v_add_u32_e32 v47, 0x18c8, v35
	v_add_u32_e32 v48, 0x1ce0, v35
	v_add_u32_e32 v49, 0x1ce8, v35
	s_mov_b32 s28, 0xfffe3
	s_movk_i32 s29, 0x63
	v_lshlrev_b32_e32 v20, 1, v2
	v_lshlrev_b32_e32 v50, 2, v6
	s_movk_i32 s30, 0xff
	s_movk_i32 s31, 0x2bf
	s_mov_b32 s33, 0xc000
	s_mov_b32 s34, 0x18000
	s_mov_b32 s35, 0x24000
	s_mov_b32 s36, 0x30000
	s_mov_b32 s37, 0x3c000
	s_mov_b32 s38, 0x48000
	s_mov_b32 s39, 0x54000
	s_branch .LBB0_19
.LBB0_18:
	s_add_i32 s20, s20, s21
	s_cmpk_gt_i32 s20, 0x11ff
	s_cbranch_scc1 .LBB0_56

.LBB0_667:
	s_abs_i32 s4, s68
	v_cvt_f32_u32_e32 v0, s4
	s_sub_i32 s5, 0, s4
	v_rcp_iflag_f32_e32 v0, v0
	s_nop 0
	v_mul_f32_e32 v0, 0x4f7ffffe, v0
	v_cvt_u32_f32_e32 v0, v0
	s_nop 0
	v_readfirstlane_b32 s6, v0
	s_mul_i32 s5, s5, s6
	s_mul_hi_u32 s5, s6, s5
	s_add_i32 s6, s6, s5
	s_mul_hi_u32 s5, s6, 0x180
	s_mul_i32 s5, s5, s4
	s_sub_i32 s5, 0x180, s5
	s_sub_i32 s6, s5, s4
	s_cmp_ge_u32 s5, s4
	s_cselect_b32 s5, s6, s5
	s_sub_i32 s6, s5, s4
	s_cmp_ge_u32 s5, s4
	s_cselect_b32 s4, s6, s5
	s_cmp_lt_i32 s69, s4
	s_cbranch_scc1 .LBB0_728
	s_ashr_i32 s5, s70, 6
	s_mul_i32 s16, s76, 0xab40
	s_sub_i32 s7, s69, s4
	s_add_i32 s6, s5, s16
	s_lshl_b32 s7, s7, 3
	s_add_i32 s6, s6, s7
	s_addk_i32 s16, 0x4000
	s_movk_i32 s17, 0x1400
	s_cmp_eq_u32 s56, 0
	s_cselect_b32 s17, 0xc00, s17
	s_add_i32 s17, s6, s17
	s_cmp_ge_i32 s17, s16
	s_cbranch_scc1 .LBB0_728
	s_sub_i32 s4, s68, s4
	s_lshl_b32 s18, s4, 3
	s_lshl_b32 s4, s5, 14
	s_add_i32 s4, s4, 0
	s_add_u32 s19, s14, 0x10612000
	s_addc_u32 s20, s15, 0
	s_add_u32 s21, s14, 0x5612000
	s_addc_u32 s22, s15, 0
	s_add_u32 s23, s14, 0x4612000
	s_addc_u32 s24, s15, 0
	s_add_u32 s25, s14, 0x3e12000
	s_addc_u32 s26, s15, 0
	s_add_u32 s27, s14, 0x3812000
	s_addc_u32 s28, s15, 0
	s_add_u32 s29, s14, 0x2e12000
	v_bfe_u32 v10, v226, 3, 3
	s_addc_u32 s30, s15, 0
	v_lshlrev_b32_e32 v0, 2, v226
	v_and_b32_e32 v3, 7, v226
	v_lshlrev_b32_e32 v6, 2, v10
	s_add_u32 s31, s14, 0x1e12000
	v_and_b32_e32 v0, 28, v0
	v_lshl_add_u32 v4, v3, 4, s4
	v_mul_u32_u24_e32 v5, 0x84, v10
	v_lshlrev_b32_e32 v2, 3, v3
	v_mul_u32_u24_e32 v3, 0x420, v3
	v_and_b32_e32 v14, 16, v6
	s_addc_u32 s33, s15, 0
	v_or_b32_e32 v11, 8, v10
	v_or_b32_e32 v12, 16, v10
	v_or_b32_e32 v13, 24, v10
	v_add3_u32 v15, s4, v3, v6
	v_or_b32_e32 v16, 4, v14
	v_or_b32_e32 v17, 8, v14
	v_or_b32_e32 v18, 12, v6
	v_lshlrev_b32_e32 v0, 2, v0
	v_add_u32_e32 v19, v4, v5
	v_lshlrev_b32_e32 v6, 1, v2
	s_mov_b32 s99, 0
	s_branch .LBB0_672
